# stack + CW_WAR sample taken during the GEMM2->GEMM3 panel sync (skips the separate poll)
# baseline (speedup 1.0000x reference)
.LBB0_461:
	s_or_b64 exec, exec, s[12:13]
	v_mov_b32_e32 v0, 0
	s_mov_b32 s100, 0
	v_readlane_b32 s98, v251, 24
	s_cmp_lg_u32 s98, 0
	s_cbranch_scc1 .Lfp_orig_1
	buffer_inv sc1
	v_mov_b32_e32 v252, 0
	v_mov_b32_e32 v253, 0x8000
	global_load_dword v253, v253, s[54:55] offset:256 sc1
	s_mov_b32 s98, 0

.Lfp_done_1:
	v_readfirstlane_b32 s99, v253
	s_cmp_ge_u32 s99, s58
	s_cselect_b32 s100, 1, 0
	s_branch .LBB0_475

.LBB0_477:
	s_cmp_lt_i32 s68, 8
	s_cselect_b64 s[6:7], -1, 0
	s_and_b64 s[6:7], s[6:7], s[4:5]
	s_andn2_b64 vcc, exec, s[6:7]
	s_cbranch_vccnz .LBB0_527
	v_readlane_b32 s4, v251, 0
	v_readlane_b32 s5, v251, 1
	s_andn2_b64 vcc, exec, s[4:5]
	s_cbranch_vccnz .LBB0_493
	v_mbcnt_lo_u32_b32 v0, -1, 0
	v_mbcnt_hi_u32_b32 v0, -1, v0
	s_nop 0
	v_cmp_eq_u32_e32 vcc, 0, v0
	s_and_saveexec_b64 s[4:5], vcc
	s_cbranch_execz .LBB0_492
	s_cmp_eq_u32 s100, 1
	s_cbranch_scc1 .LBB0_492
	v_mov_b32_e32 v0, 0x8000
	global_load_dword v0, v0, s[54:55] offset:256 sc1
	s_add_u32 s10, s54, 0x8100
	s_addc_u32 s11, s55, 0
	s_waitcnt vmcnt(0)
	v_cmp_le_u32_e32 vcc, s58, v0
	s_cbranch_vccnz .LBB0_492
	s_add_u32 s8, s54, 0x4200
	s_addc_u32 s9, s55, 0
	s_mov_b32 s14, 1
	v_mov_b32_e32 v0, 0
	s_branch .LBB0_483
